# only the split-K slab dump (kind 16) with lane-transposed stores; on top of v34
# baseline (speedup 1.0000x reference)
; __device__ __forceinline__ void epilogue(const Params& p, const Unit& u, const f32x4 (&acc)[2][2][4][2], int wr, int wc, int fr, int fq) {
;     ...
;   } else {
;     const float* x1 = (const float*)(ws + WS_X1);
;     float* yo = (float*)(ws + WS_YPRE);
;     const int cb = u.pn * 256 + ct0;
; #pragma unroll
;     for (int ai = 0; ai < 2; ++ai)
; #pragma unroll
;       for (int mp = 0; mp < 2; ++mp) {
;         f32x4 xv[2][2][2];
; #pragma unroll
;         for (int mm = 0; mm < 2; ++mm) {
;           const size_t row = (size_t)(row0 + ai * 128 + (mp * 2 + mm) * 16);
; #pragma unroll
;           for (int bj = 0; bj < 2; ++bj)
; #pragma unroll
;             for (int n = 0; n < 2; ++n) xv[mm][bj][n] = *(const f32x4*)(x1 + row * 2048 + cb + bj * 128 + n * 16);
;         }
; #pragma unroll
;         for (int mm = 0; mm < 2; ++mm) {
;           const size_t row = (size_t)(row0 + ai * 128 + (mp * 2 + mm) * 16);
; #pragma unroll
;           for (int bj = 0; bj < 2; ++bj)
; #pragma unroll
;             for (int n = 0; n < 2; ++n) *(f32x4*)(yo + row * 2048 + cb + bj * 128 + n * 16) = xv[mm][bj][n] * ALPHA + acc[ai][bj][mp * 2 + mm][n];
;         }
;       }
;   }
.LBB0_357:
	s_cmp_lt_u32 s76, 17
	s_mov_b64 s[36:37], -1
	s_cbranch_scc0 .LBB0_363
	s_cmp_lg_u32 s76, 16
	s_cbranch_scc0 .LBB0_360
	v_lshl_or_b32 v132, s78, 8, v174
	v_ashrrev_i32_e32 v133, 31, v132
	v_readlane_b32 s34, v254, 30
	v_lshlrev_b64 v[134:135], 2, v[132:133]
	v_readlane_b32 s35, v254, 31
	v_ashrrev_i32_e32 v67, 31, v66
	v_or_b32_e32 v152, 16, v66
	v_lshl_add_u64 v[132:133], s[34:35], 0, v[134:135]
	v_readlane_b32 s34, v252, 57
	v_readlane_b32 s35, v252, 58
	v_ashrrev_i32_e32 v153, 31, v152
	v_lshlrev_b64 v[166:167], 13, v[152:153]
	v_lshl_add_u64 v[164:165], s[34:35], 0, v[134:135]
	v_lshlrev_b64 v[134:135], 13, v[66:67]
	v_lshl_add_u64 v[148:149], v[132:133], 0, v[134:135]
	global_load_dwordx4 v[136:139], v[148:149], off
	global_load_dwordx4 v[140:143], v[148:149], off offset:64
	global_load_dwordx4 v[144:147], v[148:149], off offset:512
	s_nop 0
	global_load_dwordx4 v[148:151], v[148:149], off offset:576
	v_lshl_add_u64 v[196:197], v[132:133], 0, v[166:167]
	global_load_dwordx4 v[152:155], v[196:197], off
	global_load_dwordx4 v[156:159], v[196:197], off offset:64
	global_load_dwordx4 v[160:163], v[196:197], off offset:512
	s_nop 0
	global_load_dwordx4 v[196:199], v[196:197], off offset:576
	v_lshl_add_u64 v[200:201], v[164:165], 0, v[134:135]
	s_mov_b64 s[34:35], 0x100000
	s_mov_b64 s[36:37], 0x140000
	s_waitcnt vmcnt(0)
	v_pk_fma_f32 v[138:139], v[138:139], s[2:3], v[130:131] op_sel_hi:[1,0,1]
	v_pk_fma_f32 v[136:137], v[136:137], s[2:3], v[128:129] op_sel_hi:[1,0,1]
	global_store_dwordx4 v[200:201], v[136:139], off
	s_nop 1
	v_pk_fma_f32 v[138:139], v[142:143], s[2:3], v[126:127] op_sel_hi:[1,0,1]
	v_pk_fma_f32 v[136:137], v[140:141], s[2:3], v[124:125] op_sel_hi:[1,0,1]
	global_store_dwordx4 v[200:201], v[136:139], off offset:64
	v_lshl_add_u64 v[140:141], v[164:165], 0, v[166:167]
	s_nop 0
	v_pk_fma_f32 v[138:139], v[146:147], s[2:3], v[98:99] op_sel_hi:[1,0,1]
	v_pk_fma_f32 v[136:137], v[144:145], s[2:3], v[96:97] op_sel_hi:[1,0,1]
	global_store_dwordx4 v[200:201], v[136:139], off offset:512
	s_nop 1
	v_pk_fma_f32 v[138:139], v[150:151], s[2:3], v[94:95] op_sel_hi:[1,0,1]
	v_pk_fma_f32 v[136:137], v[148:149], s[2:3], v[92:93] op_sel_hi:[1,0,1]
	global_store_dwordx4 v[200:201], v[136:139], off offset:576
	s_nop 1
	v_pk_fma_f32 v[138:139], v[154:155], s[2:3], v[122:123] op_sel_hi:[1,0,1]
	v_pk_fma_f32 v[136:137], v[152:153], s[2:3], v[120:121] op_sel_hi:[1,0,1]
	global_store_dwordx4 v[140:141], v[136:139], off
	v_or_b32_e32 v152, 48, v66
	v_ashrrev_i32_e32 v153, 31, v152
	v_pk_fma_f32 v[138:139], v[158:159], s[2:3], v[118:119] op_sel_hi:[1,0,1]
	v_pk_fma_f32 v[136:137], v[156:157], s[2:3], v[116:117] op_sel_hi:[1,0,1]
	global_store_dwordx4 v[140:141], v[136:139], off offset:64
	v_lshlrev_b64 v[200:201], 13, v[152:153]
	s_nop 0
	v_pk_fma_f32 v[138:139], v[162:163], s[2:3], v[90:91] op_sel_hi:[1,0,1]
	v_pk_fma_f32 v[136:137], v[160:161], s[2:3], v[88:89] op_sel_hi:[1,0,1]
	global_store_dwordx4 v[140:141], v[136:139], off offset:512
	s_nop 1
	v_pk_fma_f32 v[138:139], v[198:199], s[2:3], v[86:87] op_sel_hi:[1,0,1]
	v_pk_fma_f32 v[136:137], v[196:197], s[2:3], v[84:85] op_sel_hi:[1,0,1]
	global_store_dwordx4 v[140:141], v[136:139], off offset:576
	v_lshl_add_u64 v[196:197], v[132:133], 0, v[200:201]
	s_nop 0
	v_or_b32_e32 v136, 32, v66
	v_ashrrev_i32_e32 v137, 31, v136
	v_lshlrev_b64 v[166:167], 13, v[136:137]
	v_lshl_add_u64 v[148:149], v[132:133], 0, v[166:167]
	global_load_dwordx4 v[136:139], v[148:149], off
	global_load_dwordx4 v[140:143], v[148:149], off offset:64
	global_load_dwordx4 v[144:147], v[148:149], off offset:512
	s_nop 0
	global_load_dwordx4 v[148:151], v[148:149], off offset:576
	s_nop 0
	global_load_dwordx4 v[152:155], v[196:197], off
	global_load_dwordx4 v[156:159], v[196:197], off offset:64
	global_load_dwordx4 v[160:163], v[196:197], off offset:512
	s_nop 0
	global_load_dwordx4 v[196:199], v[196:197], off offset:576
	v_lshl_add_u64 v[166:167], v[164:165], 0, v[166:167]
	s_waitcnt vmcnt(0)
	v_pk_fma_f32 v[138:139], v[138:139], s[2:3], v[114:115] op_sel_hi:[1,0,1]
	v_pk_fma_f32 v[136:137], v[136:137], s[2:3], v[112:113] op_sel_hi:[1,0,1]
	global_store_dwordx4 v[166:167], v[136:139], off
	s_nop 1
	v_pk_fma_f32 v[138:139], v[142:143], s[2:3], v[110:111] op_sel_hi:[1,0,1]
	v_pk_fma_f32 v[136:137], v[140:141], s[2:3], v[108:109] op_sel_hi:[1,0,1]
	global_store_dwordx4 v[166:167], v[136:139], off offset:64
	v_lshl_add_u64 v[140:141], v[164:165], 0, v[200:201]
	s_nop 0
	v_pk_fma_f32 v[138:139], v[146:147], s[2:3], v[82:83] op_sel_hi:[1,0,1]
	v_pk_fma_f32 v[136:137], v[144:145], s[2:3], v[80:81] op_sel_hi:[1,0,1]
	global_store_dwordx4 v[166:167], v[136:139], off offset:512
	s_nop 1
	v_pk_fma_f32 v[138:139], v[150:151], s[2:3], v[78:79] op_sel_hi:[1,0,1]
	v_pk_fma_f32 v[136:137], v[148:149], s[2:3], v[76:77] op_sel_hi:[1,0,1]
	global_store_dwordx4 v[166:167], v[136:139], off offset:576
	v_lshl_add_u64 v[166:167], v[134:135], 0, s[34:35]
	v_lshl_add_u64 v[148:149], v[132:133], 0, v[166:167]
	v_pk_fma_f32 v[138:139], v[154:155], s[2:3], v[106:107] op_sel_hi:[1,0,1]
	v_pk_fma_f32 v[136:137], v[152:153], s[2:3], v[104:105] op_sel_hi:[1,0,1]
	global_store_dwordx4 v[140:141], v[136:139], off
	s_mov_b64 s[34:35], 0x120000
	v_lshl_add_u64 v[200:201], v[134:135], 0, s[34:35]
	v_pk_fma_f32 v[138:139], v[158:159], s[2:3], v[102:103] op_sel_hi:[1,0,1]
	v_pk_fma_f32 v[136:137], v[156:157], s[2:3], v[100:101] op_sel_hi:[1,0,1]
	global_store_dwordx4 v[140:141], v[136:139], off offset:64
	v_lshl_add_u64 v[166:167], v[164:165], 0, v[166:167]
	s_mov_b64 s[34:35], 0x160000
	v_pk_fma_f32 v[138:139], v[162:163], s[2:3], v[74:75] op_sel_hi:[1,0,1]
	v_pk_fma_f32 v[136:137], v[160:161], s[2:3], v[72:73] op_sel_hi:[1,0,1]
	global_store_dwordx4 v[140:141], v[136:139], off offset:512
	s_nop 1
	v_pk_fma_f32 v[138:139], v[198:199], s[2:3], v[70:71] op_sel_hi:[1,0,1]
	v_pk_fma_f32 v[136:137], v[196:197], s[2:3], v[68:69] op_sel_hi:[1,0,1]
	global_store_dwordx4 v[140:141], v[136:139], off offset:576
	global_load_dwordx4 v[136:139], v[148:149], off
	s_nop 0
	global_load_dwordx4 v[140:143], v[148:149], off offset:64
	global_load_dwordx4 v[144:147], v[148:149], off offset:512
	s_nop 0
	global_load_dwordx4 v[148:151], v[148:149], off offset:576
	v_lshl_add_u64 v[196:197], v[132:133], 0, v[200:201]
	global_load_dwordx4 v[152:155], v[196:197], off
	global_load_dwordx4 v[156:159], v[196:197], off offset:64
	global_load_dwordx4 v[160:163], v[196:197], off offset:512
	s_nop 0
	global_load_dwordx4 v[196:199], v[196:197], off offset:576
	s_waitcnt vmcnt(0)
; __device__ __forceinline__ void epilogue(const Params& p, const Unit& u, const f32x4 (&acc)[2][2][4][2], int wr, int wc, int fr, int fq) {
;     ...
;   } else if (kind == 16) {
;     float* pt = (float*)(ws + WS_PART) + (size_t)u.pm * 65536;
;     ...
;         f32x4 xv[2][2][2];
; #pragma unroll
;         for (int mm = 0; mm < 2; ++mm) {
;           const size_t row = (size_t)(row0 + ai * 128 + (mp * 2 + mm) * 16);
; #pragma unroll
;           for (int bj = 0; bj < 2; ++bj)
; #pragma unroll
;             for (int n = 0; n < 2; ++n) xv[mm][bj][n] = *(const f32x4*)(x1 + row * 2048 + cb + bj * 128 + n * 16);
;         }
; #pragma unroll
;         for (int mm = 0; mm < 2; ++mm) {
;           const size_t row = (size_t)(row0 + ai * 128 + (mp * 2 + mm) * 16);
; #pragma unroll
;           for (int bj = 0; bj < 2; ++bj)
; #pragma unroll
;             for (int n = 0; n < 2; ++n) *(f32x4*)(yo + row * 2048 + cb + bj * 128 + n * 16) = xv[mm][bj][n] * ALPHA + acc[ai][bj][mp * 2 + mm][n];
;         }
;       }
;   }
	v_pk_fma_f32 v[138:139], v[138:139], s[2:3], v[62:63] op_sel_hi:[1,0,1]
	v_pk_fma_f32 v[136:137], v[136:137], s[2:3], v[60:61] op_sel_hi:[1,0,1]
	global_store_dwordx4 v[166:167], v[136:139], off
	s_nop 1
	v_pk_fma_f32 v[138:139], v[142:143], s[2:3], v[58:59] op_sel_hi:[1,0,1]
	v_pk_fma_f32 v[136:137], v[140:141], s[2:3], v[56:57] op_sel_hi:[1,0,1]
	global_store_dwordx4 v[166:167], v[136:139], off offset:64
	v_lshl_add_u64 v[140:141], v[164:165], 0, v[200:201]
	s_nop 0
	v_pk_fma_f32 v[138:139], v[146:147], s[2:3], v[30:31] op_sel_hi:[1,0,1]
	v_pk_fma_f32 v[136:137], v[144:145], s[2:3], v[28:29] op_sel_hi:[1,0,1]
	global_store_dwordx4 v[166:167], v[136:139], off offset:512
	s_nop 1
	v_pk_fma_f32 v[138:139], v[150:151], s[2:3], v[26:27] op_sel_hi:[1,0,1]
	v_pk_fma_f32 v[136:137], v[148:149], s[2:3], v[24:25] op_sel_hi:[1,0,1]
	global_store_dwordx4 v[166:167], v[136:139], off offset:576
	v_lshl_add_u64 v[166:167], v[134:135], 0, s[36:37]
	s_mov_b64 s[36:37], 0
	v_pk_fma_f32 v[138:139], v[154:155], s[2:3], v[54:55] op_sel_hi:[1,0,1]
	v_pk_fma_f32 v[136:137], v[152:153], s[2:3], v[52:53] op_sel_hi:[1,0,1]
	global_store_dwordx4 v[140:141], v[136:139], off
	s_nop 1
	v_pk_fma_f32 v[138:139], v[158:159], s[2:3], v[50:51] op_sel_hi:[1,0,1]
	v_pk_fma_f32 v[136:137], v[156:157], s[2:3], v[48:49] op_sel_hi:[1,0,1]
	global_store_dwordx4 v[140:141], v[136:139], off offset:64
	s_nop 1
	v_pk_fma_f32 v[138:139], v[162:163], s[2:3], v[22:23] op_sel_hi:[1,0,1]
	v_pk_fma_f32 v[136:137], v[160:161], s[2:3], v[20:21] op_sel_hi:[1,0,1]
	global_store_dwordx4 v[140:141], v[136:139], off offset:512
	s_nop 1
	v_pk_fma_f32 v[138:139], v[198:199], s[2:3], v[18:19] op_sel_hi:[1,0,1]
	v_pk_fma_f32 v[136:137], v[196:197], s[2:3], v[16:17] op_sel_hi:[1,0,1]
	global_store_dwordx4 v[140:141], v[136:139], off offset:576
	v_lshl_add_u64 v[196:197], v[134:135], 0, s[34:35]
	s_nop 0
	v_lshl_add_u64 v[136:137], v[132:133], 0, v[166:167]
	global_load_dwordx4 v[160:163], v[136:137], off
	global_load_dwordx4 v[152:155], v[136:137], off offset:64
	global_load_dwordx4 v[156:159], v[136:137], off offset:512
	global_load_dwordx4 v[144:147], v[136:137], off offset:576
	v_lshl_add_u64 v[132:133], v[132:133], 0, v[196:197]
	global_load_dwordx4 v[148:151], v[132:133], off
	global_load_dwordx4 v[140:143], v[132:133], off offset:64
	global_load_dwordx4 v[136:139], v[132:133], off offset:512
	s_nop 0
	global_load_dwordx4 v[132:135], v[132:133], off offset:576
	v_lshl_add_u64 v[166:167], v[164:165], 0, v[166:167]
	s_waitcnt vmcnt(0)
	v_pk_fma_f32 v[162:163], v[162:163], s[2:3], v[46:47] op_sel_hi:[1,0,1]
	v_pk_fma_f32 v[154:155], v[154:155], s[2:3], v[42:43] op_sel_hi:[1,0,1]
	v_pk_fma_f32 v[152:153], v[152:153], s[2:3], v[40:41] op_sel_hi:[1,0,1]
	global_store_dwordx4 v[166:167], v[152:155], off offset:64
	v_pk_fma_f32 v[146:147], v[146:147], s[2:3], v[10:11] op_sel_hi:[1,0,1]
	v_pk_fma_f32 v[144:145], v[144:145], s[2:3], v[8:9] op_sel_hi:[1,0,1]
	v_pk_fma_f32 v[154:155], v[158:159], s[2:3], v[14:15] op_sel_hi:[1,0,1]
	v_pk_fma_f32 v[152:153], v[156:157], s[2:3], v[12:13] op_sel_hi:[1,0,1]
	v_pk_fma_f32 v[160:161], v[160:161], s[2:3], v[44:45] op_sel_hi:[1,0,1]
	global_store_dwordx4 v[166:167], v[152:155], off offset:512
	global_store_dwordx4 v[166:167], v[144:147], off offset:576
	v_pk_fma_f32 v[142:143], v[142:143], s[2:3], v[34:35] op_sel_hi:[1,0,1]
	v_lshl_add_u64 v[152:153], v[164:165], 0, v[196:197]
	v_pk_fma_f32 v[146:147], v[150:151], s[2:3], v[38:39] op_sel_hi:[1,0,1]
	v_pk_fma_f32 v[144:145], v[148:149], s[2:3], v[36:37] op_sel_hi:[1,0,1]
	v_pk_fma_f32 v[140:141], v[140:141], s[2:3], v[32:33] op_sel_hi:[1,0,1]
	v_pk_fma_f32 v[138:139], v[138:139], s[2:3], v[6:7] op_sel_hi:[1,0,1]
	v_pk_fma_f32 v[136:137], v[136:137], s[2:3], v[4:5] op_sel_hi:[1,0,1]
	v_pk_fma_f32 v[134:135], v[134:135], s[2:3], v[2:3] op_sel_hi:[1,0,1]
	v_pk_fma_f32 v[132:133], v[132:133], s[2:3], v[0:1] op_sel_hi:[1,0,1]
	global_store_dwordx4 v[166:167], v[160:163], off
	global_store_dwordx4 v[152:153], v[144:147], off
	global_store_dwordx4 v[152:153], v[140:143], off offset:64
	global_store_dwordx4 v[152:153], v[136:139], off offset:512
	global_store_dwordx4 v[152:153], v[132:135], off offset:576
.LBB0_360:
	s_andn2_b64 vcc, exec, s[36:37]
	s_cbranch_vccnz .LBB0_362
	s_branch .Le16_ep
; __device__ __forceinline__ void epilogue(const Params& p, const Unit& u, const f32x4 (&acc)[2][2][4][2], int wr, int wc, int fr, int fq) {
;     ...
;   } else if (kind == 16) {
;     float* pt = (float*)(ws + WS_PART) + (size_t)u.pm * 65536;
; #pragma unroll
;     for (int ai = 0; ai < 2; ++ai)
; #pragma unroll
;       for (int m = 0; m < 4; ++m) {
;         float* rp = pt + (wr * 64 + fr + ai * 128 + m * 16) * 256 + ct0;
; #pragma unroll
;         for (int bj = 0; bj < 2; ++bj)
; #pragma unroll
;           for (int n = 0; n < 2; ++n) *(f32x4*)(rp + bj * 128 + n * 16) = acc[ai][bj][m][n];
;       }
.Le16_ep:
	s_add_u32 s36, s24, 0x1f909000
	s_addc_u32 s37, s25, 0
	v_lshrrev_b32_e32 v64, 2, v230
	v_and_b32_e32 v67, 3, v230
	v_lshlrev_b32_e32 v224, 6, v67
	v_lshl_add_u32 v224, v64, 2, v224
	v_and_b32_e32 v225, 64, v169
	v_add_u32_e32 v225, v225, v64
	v_lshl_add_u32 v225, s48, 8, v225
	v_lshlrev_b32_e32 v225, 10, v225
	v_and_b32_e32 v232, 0x60, v174
	v_lshl_add_u32 v232, v67, 2, v232
	v_lshl_add_u32 v225, v232, 2, v225
	ds_bpermute_b32 v128, v224, v128
	ds_bpermute_b32 v129, v224, v129
	ds_bpermute_b32 v130, v224, v130
	ds_bpermute_b32 v131, v224, v131
	ds_bpermute_b32 v124, v224, v124
	ds_bpermute_b32 v125, v224, v125
	ds_bpermute_b32 v126, v224, v126
	ds_bpermute_b32 v127, v224, v127
	s_waitcnt lgkmcnt(4)
	global_store_dwordx4 v225, v[128:131], s[36:37] offset:0
	ds_bpermute_b32 v96, v224, v96
	ds_bpermute_b32 v97, v224, v97
	ds_bpermute_b32 v98, v224, v98
	ds_bpermute_b32 v99, v224, v99
	s_waitcnt lgkmcnt(4)
	global_store_dwordx4 v225, v[124:127], s[36:37] offset:64
	ds_bpermute_b32 v92, v224, v92
	ds_bpermute_b32 v93, v224, v93
	ds_bpermute_b32 v94, v224, v94
	ds_bpermute_b32 v95, v224, v95
	s_waitcnt lgkmcnt(4)
	global_store_dwordx4 v225, v[96:99], s[36:37] offset:512
	ds_bpermute_b32 v120, v224, v120
	ds_bpermute_b32 v121, v224, v121
	ds_bpermute_b32 v122, v224, v122
	ds_bpermute_b32 v123, v224, v123
	s_waitcnt lgkmcnt(4)
	global_store_dwordx4 v225, v[92:95], s[36:37] offset:576
	v_add_u32_e32 v225, 0x4000, v225
	ds_bpermute_b32 v116, v224, v116
	ds_bpermute_b32 v117, v224, v117
	ds_bpermute_b32 v118, v224, v118
	ds_bpermute_b32 v119, v224, v119
	s_waitcnt lgkmcnt(4)
	global_store_dwordx4 v225, v[120:123], s[36:37] offset:0
	ds_bpermute_b32 v88, v224, v88
	ds_bpermute_b32 v89, v224, v89
	ds_bpermute_b32 v90, v224, v90
	ds_bpermute_b32 v91, v224, v91
	s_waitcnt lgkmcnt(4)
	global_store_dwordx4 v225, v[116:119], s[36:37] offset:64
	ds_bpermute_b32 v84, v224, v84
	ds_bpermute_b32 v85, v224, v85
	ds_bpermute_b32 v86, v224, v86
	ds_bpermute_b32 v87, v224, v87
	s_waitcnt lgkmcnt(4)
	global_store_dwordx4 v225, v[88:91], s[36:37] offset:512
	ds_bpermute_b32 v112, v224, v112
	ds_bpermute_b32 v113, v224, v113
	ds_bpermute_b32 v114, v224, v114
	ds_bpermute_b32 v115, v224, v115
	s_waitcnt lgkmcnt(4)
	global_store_dwordx4 v225, v[84:87], s[36:37] offset:576
	v_add_u32_e32 v225, 0x4000, v225
	ds_bpermute_b32 v108, v224, v108
	ds_bpermute_b32 v109, v224, v109
	ds_bpermute_b32 v110, v224, v110
	ds_bpermute_b32 v111, v224, v111
	s_waitcnt lgkmcnt(4)
	global_store_dwordx4 v225, v[112:115], s[36:37] offset:0
	ds_bpermute_b32 v80, v224, v80
	ds_bpermute_b32 v81, v224, v81
	ds_bpermute_b32 v82, v224, v82
	ds_bpermute_b32 v83, v224, v83
	s_waitcnt lgkmcnt(4)
	global_store_dwordx4 v225, v[108:111], s[36:37] offset:64
	ds_bpermute_b32 v76, v224, v76
	ds_bpermute_b32 v77, v224, v77
	ds_bpermute_b32 v78, v224, v78
	ds_bpermute_b32 v79, v224, v79
	s_waitcnt lgkmcnt(4)
	global_store_dwordx4 v225, v[80:83], s[36:37] offset:512
	ds_bpermute_b32 v104, v224, v104
	ds_bpermute_b32 v105, v224, v105
	ds_bpermute_b32 v106, v224, v106
	ds_bpermute_b32 v107, v224, v107
	s_waitcnt lgkmcnt(4)
	global_store_dwordx4 v225, v[76:79], s[36:37] offset:576
	v_add_u32_e32 v225, 0x4000, v225
	ds_bpermute_b32 v100, v224, v100
	ds_bpermute_b32 v101, v224, v101
	ds_bpermute_b32 v102, v224, v102
	ds_bpermute_b32 v103, v224, v103
	s_waitcnt lgkmcnt(4)
	global_store_dwordx4 v225, v[104:107], s[36:37] offset:0
	ds_bpermute_b32 v72, v224, v72
	ds_bpermute_b32 v73, v224, v73
	ds_bpermute_b32 v74, v224, v74
	ds_bpermute_b32 v75, v224, v75
	s_waitcnt lgkmcnt(4)
	global_store_dwordx4 v225, v[100:103], s[36:37] offset:64
	ds_bpermute_b32 v68, v224, v68
	ds_bpermute_b32 v69, v224, v69
	ds_bpermute_b32 v70, v224, v70
	ds_bpermute_b32 v71, v224, v71
	s_waitcnt lgkmcnt(4)
	global_store_dwordx4 v225, v[72:75], s[36:37] offset:512
	ds_bpermute_b32 v60, v224, v60
	ds_bpermute_b32 v61, v224, v61
	ds_bpermute_b32 v62, v224, v62
	ds_bpermute_b32 v63, v224, v63
	s_waitcnt lgkmcnt(4)
	global_store_dwordx4 v225, v[68:71], s[36:37] offset:576
	v_add_u32_e32 v225, 0x14000, v225
	ds_bpermute_b32 v56, v224, v56
	ds_bpermute_b32 v57, v224, v57
	ds_bpermute_b32 v58, v224, v58
	ds_bpermute_b32 v59, v224, v59
	s_waitcnt lgkmcnt(4)
	global_store_dwordx4 v225, v[60:63], s[36:37] offset:0
	ds_bpermute_b32 v28, v224, v28
	ds_bpermute_b32 v29, v224, v29
	ds_bpermute_b32 v30, v224, v30
	ds_bpermute_b32 v31, v224, v31
	s_waitcnt lgkmcnt(4)
	global_store_dwordx4 v225, v[56:59], s[36:37] offset:64
	ds_bpermute_b32 v24, v224, v24
	ds_bpermute_b32 v25, v224, v25
	ds_bpermute_b32 v26, v224, v26
	ds_bpermute_b32 v27, v224, v27
	s_waitcnt lgkmcnt(4)
	global_store_dwordx4 v225, v[28:31], s[36:37] offset:512
	ds_bpermute_b32 v52, v224, v52
	ds_bpermute_b32 v53, v224, v53
	ds_bpermute_b32 v54, v224, v54
	ds_bpermute_b32 v55, v224, v55
	s_waitcnt lgkmcnt(4)
; __device__ __forceinline__ void epilogue(const Params& p, const Unit& u, const f32x4 (&acc)[2][2][4][2], int wr, int wc, int fr, int fq) {
;     ...
;   } else if (kind == 16) {
;     float* pt = (float*)(ws + WS_PART) + (size_t)u.pm * 65536;
; #pragma unroll
;     for (int ai = 0; ai < 2; ++ai)
; #pragma unroll
;       for (int m = 0; m < 4; ++m) {
;         float* rp = pt + (wr * 64 + fr + ai * 128 + m * 16) * 256 + ct0;
; #pragma unroll
;         for (int bj = 0; bj < 2; ++bj)
; #pragma unroll
;           for (int n = 0; n < 2; ++n) *(f32x4*)(rp + bj * 128 + n * 16) = acc[ai][bj][m][n];
;       }
	global_store_dwordx4 v225, v[24:27], s[36:37] offset:576
	v_add_u32_e32 v225, 0x4000, v225
	ds_bpermute_b32 v48, v224, v48
	ds_bpermute_b32 v49, v224, v49
	ds_bpermute_b32 v50, v224, v50
	ds_bpermute_b32 v51, v224, v51
	s_waitcnt lgkmcnt(4)
	global_store_dwordx4 v225, v[52:55], s[36:37] offset:0
	ds_bpermute_b32 v20, v224, v20
	ds_bpermute_b32 v21, v224, v21
	ds_bpermute_b32 v22, v224, v22
	ds_bpermute_b32 v23, v224, v23
	s_waitcnt lgkmcnt(4)
	global_store_dwordx4 v225, v[48:51], s[36:37] offset:64
	ds_bpermute_b32 v16, v224, v16
	ds_bpermute_b32 v17, v224, v17
	ds_bpermute_b32 v18, v224, v18
	ds_bpermute_b32 v19, v224, v19
	s_waitcnt lgkmcnt(4)
	global_store_dwordx4 v225, v[20:23], s[36:37] offset:512
	ds_bpermute_b32 v44, v224, v44
	ds_bpermute_b32 v45, v224, v45
	ds_bpermute_b32 v46, v224, v46
	ds_bpermute_b32 v47, v224, v47
	s_waitcnt lgkmcnt(4)
	global_store_dwordx4 v225, v[16:19], s[36:37] offset:576
	v_add_u32_e32 v225, 0x4000, v225
	ds_bpermute_b32 v40, v224, v40
	ds_bpermute_b32 v41, v224, v41
	ds_bpermute_b32 v42, v224, v42
	ds_bpermute_b32 v43, v224, v43
	s_waitcnt lgkmcnt(4)
	global_store_dwordx4 v225, v[44:47], s[36:37] offset:0
	ds_bpermute_b32 v12, v224, v12
	ds_bpermute_b32 v13, v224, v13
	ds_bpermute_b32 v14, v224, v14
	ds_bpermute_b32 v15, v224, v15
	s_waitcnt lgkmcnt(4)
	global_store_dwordx4 v225, v[40:43], s[36:37] offset:64
	ds_bpermute_b32 v8, v224, v8
	ds_bpermute_b32 v9, v224, v9
	ds_bpermute_b32 v10, v224, v10
	ds_bpermute_b32 v11, v224, v11
	s_waitcnt lgkmcnt(4)
	global_store_dwordx4 v225, v[12:15], s[36:37] offset:512
	ds_bpermute_b32 v36, v224, v36
	ds_bpermute_b32 v37, v224, v37
	ds_bpermute_b32 v38, v224, v38
	ds_bpermute_b32 v39, v224, v39
	s_waitcnt lgkmcnt(4)
	global_store_dwordx4 v225, v[8:11], s[36:37] offset:576
	v_add_u32_e32 v225, 0x4000, v225
	ds_bpermute_b32 v32, v224, v32
	ds_bpermute_b32 v33, v224, v33
	ds_bpermute_b32 v34, v224, v34
	ds_bpermute_b32 v35, v224, v35
	s_waitcnt lgkmcnt(4)
	global_store_dwordx4 v225, v[36:39], s[36:37] offset:0
	ds_bpermute_b32 v4, v224, v4
	ds_bpermute_b32 v5, v224, v5
	ds_bpermute_b32 v6, v224, v6
	ds_bpermute_b32 v7, v224, v7
	s_waitcnt lgkmcnt(4)
	global_store_dwordx4 v225, v[32:35], s[36:37] offset:64
	ds_bpermute_b32 v0, v224, v0
	ds_bpermute_b32 v1, v224, v1
	ds_bpermute_b32 v2, v224, v2
	ds_bpermute_b32 v3, v224, v3
	s_waitcnt lgkmcnt(4)
	global_store_dwordx4 v225, v[4:7], s[36:37] offset:512
	s_waitcnt lgkmcnt(0)
	global_store_dwordx4 v225, v[0:3], s[36:37] offset:576
	s_branch .LBB0_987
	s_ashr_i32 s49, s48, 31
	s_lshl_b64 s[34:35], s[48:49], 18
	v_lshl_add_u64 v[132:133], v[188:189], 0, s[34:35]
	v_lshl_add_u64 v[134:135], v[176:177], 2, v[132:133]
	v_add_co_u32_e32 v136, vcc, 0x4000, v134
	global_store_dwordx4 v[134:135], v[128:131], off
	global_store_dwordx4 v[134:135], v[124:127], off offset:64
	global_store_dwordx4 v[134:135], v[96:99], off offset:512
	global_store_dwordx4 v[134:135], v[92:95], off offset:576
	v_addc_co_u32_e32 v137, vcc, 0, v135, vcc
	global_store_dwordx4 v[136:137], v[120:123], off
	global_store_dwordx4 v[136:137], v[116:119], off offset:64
	global_store_dwordx4 v[136:137], v[88:91], off offset:512
	global_store_dwordx4 v[136:137], v[84:87], off offset:576
	v_add_co_u32_e32 v136, vcc, 0x8000, v134
	s_nop 1
	v_addc_co_u32_e32 v137, vcc, 0, v135, vcc
	v_add_co_u32_e32 v134, vcc, 0xc000, v134
	global_store_dwordx4 v[136:137], v[112:115], off
	global_store_dwordx4 v[136:137], v[108:111], off offset:64
	global_store_dwordx4 v[136:137], v[80:83], off offset:512
	global_store_dwordx4 v[136:137], v[76:79], off offset:576
	v_addc_co_u32_e32 v135, vcc, 0, v135, vcc
	global_store_dwordx4 v[134:135], v[104:107], off
	global_store_dwordx4 v[134:135], v[100:103], off offset:64
	global_store_dwordx4 v[134:135], v[72:75], off offset:512
	global_store_dwordx4 v[134:135], v[68:71], off offset:576
	v_lshl_add_u64 v[134:135], v[178:179], 2, v[132:133]
	global_store_dwordx4 v[134:135], v[60:63], off
	global_store_dwordx4 v[134:135], v[56:59], off offset:64
	global_store_dwordx4 v[134:135], v[28:31], off offset:512
	global_store_dwordx4 v[134:135], v[24:27], off offset:576
	v_lshl_add_u64 v[134:135], v[180:181], 2, v[132:133]
	global_store_dwordx4 v[134:135], v[52:55], off
	global_store_dwordx4 v[134:135], v[48:51], off offset:64
	global_store_dwordx4 v[134:135], v[20:23], off offset:512
	global_store_dwordx4 v[134:135], v[16:19], off offset:576
	v_lshl_add_u64 v[134:135], v[182:183], 2, v[132:133]
	v_lshl_add_u64 v[132:133], v[184:185], 2, v[132:133]
	global_store_dwordx4 v[134:135], v[44:47], off
	global_store_dwordx4 v[134:135], v[40:43], off offset:64
	global_store_dwordx4 v[134:135], v[12:15], off offset:512
	global_store_dwordx4 v[134:135], v[8:11], off offset:576
	global_store_dwordx4 v[132:133], v[36:39], off
	global_store_dwordx4 v[132:133], v[32:35], off offset:64
	global_store_dwordx4 v[132:133], v[4:7], off offset:512
	global_store_dwordx4 v[132:133], v[0:3], off offset:576
